# h_fold row pass: bf16 row stores write-through (sc1) on top of the non-temporal x loads
# baseline (speedup 1.0000x reference)
; __device__ __forceinline__ void pass_h_fold(const float* src, const float* g, const float* mod, bf16_t* H, bf16_t* HE, bf16_t* HO) {
;     ...
;     for (int ch = gw; ch < 2048; ch += NGW) {
;         const int b = ch >> 8, sb = (ch & 255) * 4;
;         f32x4 mul[4], sh[4];
; #pragma unroll
;         for (int j = 0; j < 4; ++j) { const f32x4 gg = ((const f32x4*)g)[lane + 64 * j], sc = ((const f32x4*)(mod + (size_t)b * NMOD + DM))[lane + 64 * j];
;             mul[j] = gg * (1.0f + sc); sh[j] = ((const f32x4*)(mod + (size_t)b * NMOD))[lane + 64 * j]; }
; #pragma unroll
;         for (int half = 0; half < 2; ++half) {
;             f32x4 v[2][2][4];
; #pragma unroll
;             for (int q = 0; q < 2; ++q) { const int s = sb + half * 2 + q, pr = (s == 0) ? SEQ / 2 : SEQ - s;
;                 const f32x4* x0 = (const f32x4*)(src + (size_t)(b * SEQ + s) * DM) + lane; const f32x4* x1 = (const f32x4*)(src + (size_t)(b * SEQ + pr) * DM) + lane;
; #pragma unroll
;                 for (int j = 0; j < 4; ++j) { v[q][0][j] = x0[64 * j]; v[q][1][j] = x1[64 * j]; } }
.LBB0_99:
	v_ashrrev_i32_e32 v16, 8, v173
	v_and_b32_e32 v17, 0x3fc, v180
	v_mul_hi_i32_i24_e32 v19, 0x6000, v16
	v_mul_i32_i24_e32 v18, 0x6000, v16
	v_lshlrev_b32_e32 v20, 11, v16
	v_lshlrev_b32_e32 v16, 10, v16
	v_or_b32_e32 v22, 1, v17
	v_or_b32_e32 v23, 2, v17
	v_or_b32_e32 v37, 3, v17
	v_lshl_add_u64 v[18:19], s[34:35], 0, v[18:19]
	v_or_b32_e32 v24, v17, v20
	v_sub_u32_e32 v21, 0x800, v17
	v_cmp_eq_u32_e64 s[4:5], 0, v17
	v_or_b32_e32 v26, v22, v20
	v_or_b32_e32 v28, v17, v16
	v_or_b32_e32 v30, v22, v16
	v_or_b32_e32 v32, v23, v20
	v_or_b32_e32 v34, v37, v20
	v_lshl_add_u64 v[40:41], v[18:19], 0, s[24:25]
	v_ashrrev_i32_e32 v25, 31, v24
	v_cndmask_b32_e64 v21, v21, v181, s[4:5]
	v_add_u32_e32 v39, 0x800, v20
	v_lshl_add_u64 v[42:43], v[18:19], 0, v[96:97]
	v_ashrrev_i32_e32 v27, 31, v26
	v_ashrrev_i32_e32 v29, 31, v28
	v_ashrrev_i32_e32 v31, 31, v30
	v_ashrrev_i32_e32 v33, 31, v32
	v_ashrrev_i32_e32 v35, 31, v34
	v_lshl_add_u64 v[52:53], v[40:41], 0, v[96:97]
	v_lshl_add_u64 v[54:55], v[40:41], 0, v[108:109]
	v_lshl_add_u64 v[56:57], v[40:41], 0, v[110:111]
	v_lshl_add_u64 v[40:41], v[40:41], 0, v[112:113]
	v_lshlrev_b64 v[58:59], 12, v[24:25]
	global_load_dwordx4 v[0:3], v[106:107], off
	global_load_dwordx4 v[4:7], v[106:107], off offset:1024
	global_load_dwordx4 v[8:11], v[106:107], off offset:2048
	global_load_dwordx4 v[12:15], v[106:107], off offset:3072
	v_or_b32_e32 v36, v23, v16
	v_or_b32_e32 v38, v37, v16
	v_add_u32_e32 v44, v21, v20
	v_sub_u32_e32 v46, v39, v22
	v_sub_u32_e32 v48, v39, v23
	v_sub_u32_e32 v50, v39, v37
	global_load_dwordx4 v[20:23], v[42:43], off offset:1024
	global_load_dwordx4 v[16:19], v[42:43], off offset:2048
	v_lshlrev_b64 v[60:61], 12, v[26:27]
	v_lshlrev_b64 v[62:63], 11, v[24:25]
	v_lshlrev_b64 v[64:65], 11, v[28:29]
	v_lshlrev_b64 v[66:67], 11, v[26:27]
	v_lshlrev_b64 v[68:69], 11, v[30:31]
	v_lshlrev_b64 v[70:71], 12, v[32:33]
	v_lshlrev_b64 v[72:73], 12, v[34:35]
	global_load_dwordx4 v[130:133], v[52:53], off
	global_load_dwordx4 v[28:31], v[42:43], off
	global_load_dwordx4 v[134:137], v[56:57], off
	global_load_dwordx4 v[138:141], v[40:41], off
	global_load_dwordx4 v[142:145], v[54:55], off
	global_load_dwordx4 v[24:27], v[42:43], off offset:3072
	v_lshl_add_u64 v[40:41], v[98:99], 0, v[58:59]
	v_ashrrev_i32_e32 v37, 31, v36
	v_ashrrev_i32_e32 v39, 31, v38
	v_ashrrev_i32_e32 v45, 31, v44
	v_ashrrev_i32_e32 v47, 31, v46
	v_ashrrev_i32_e32 v49, 31, v48
	v_ashrrev_i32_e32 v51, 31, v50
	v_lshlrev_b64 v[32:33], 11, v[32:33]
	v_lshlrev_b64 v[34:35], 11, v[34:35]
	v_lshl_add_u64 v[80:81], v[98:99], 0, v[60:61]
	v_lshl_add_u64 v[152:153], v[102:103], 0, v[68:69]
	v_lshl_add_u64 v[150:151], v[104:105], 0, v[68:69]
	v_lshl_add_u64 v[148:149], v[98:99], 0, v[70:71]
	v_lshl_add_u64 v[146:147], v[98:99], 0, v[72:73]
	global_load_dwordx4 v[84:87], v[40:41], off nt
	global_load_dwordx4 v[72:75], v[40:41], off offset:1024 nt
	global_load_dwordx4 v[68:71], v[40:41], off offset:3072 nt
	global_load_dwordx4 v[76:79], v[40:41], off offset:2048 nt
	global_load_dwordx4 v[56:59], v[80:81], off nt
	v_lshlrev_b64 v[36:37], 11, v[36:37]
	v_lshlrev_b64 v[38:39], 11, v[38:39]
	v_lshlrev_b64 v[42:43], 12, v[44:45]
	v_lshlrev_b64 v[82:83], 12, v[46:47]
	v_lshl_add_u64 v[166:167], v[100:101], 0, v[62:63]
	v_lshl_add_u64 v[164:165], v[102:103], 0, v[64:65]
	v_lshl_add_u64 v[162:163], v[104:105], 0, v[64:65]
	v_lshl_add_u64 v[154:155], v[100:101], 0, v[66:67]
	v_lshlrev_b64 v[64:65], 12, v[48:49]
	v_lshlrev_b64 v[66:67], 12, v[50:51]
	v_lshl_add_u64 v[126:127], v[100:101], 0, v[32:33]
	v_lshlrev_b64 v[32:33], 11, v[48:49]
	v_lshl_add_u64 v[118:119], v[100:101], 0, v[34:35]
	v_lshlrev_b64 v[34:35], 11, v[50:51]
	global_load_dwordx4 v[60:63], v[80:81], off offset:1024 nt
	global_load_dwordx4 v[52:55], v[80:81], off offset:2048 nt
	global_load_dwordx4 v[48:51], v[80:81], off offset:3072 nt
	v_lshlrev_b64 v[44:45], 11, v[44:45]
	v_lshlrev_b64 v[46:47], 11, v[46:47]
	v_lshl_add_u64 v[124:125], v[102:103], 0, v[36:37]
	v_lshl_add_u64 v[122:123], v[104:105], 0, v[36:37]
	v_lshl_add_u64 v[116:117], v[102:103], 0, v[38:39]
	v_lshl_add_u64 v[114:115], v[104:105], 0, v[38:39]
	v_lshl_add_u64 v[36:37], v[98:99], 0, v[42:43]
	v_lshl_add_u64 v[38:39], v[98:99], 0, v[82:83]
	v_lshl_add_u64 v[168:169], v[100:101], 0, v[44:45]
	v_lshl_add_u64 v[160:161], v[100:101], 0, v[46:47]
	v_lshl_add_u64 v[158:159], v[98:99], 0, v[64:65]
	v_lshl_add_u64 v[156:157], v[98:99], 0, v[66:67]
	v_lshl_add_u64 v[128:129], v[100:101], 0, v[32:33]
	v_lshl_add_u64 v[120:121], v[100:101], 0, v[34:35]
	global_load_dwordx4 v[92:95], v[36:37], off nt
	global_load_dwordx4 v[88:91], v[36:37], off offset:1024 nt
	global_load_dwordx4 v[64:67], v[36:37], off offset:3072 nt
	global_load_dwordx4 v[80:83], v[36:37], off offset:2048 nt
	global_load_dwordx4 v[44:47], v[38:39], off nt
	global_load_dwordx4 v[40:43], v[38:39], off offset:1024 nt
	global_load_dwordx4 v[32:35], v[38:39], off offset:3072 nt
	s_nop 0
	global_load_dwordx4 v[36:39], v[38:39], off offset:2048 nt
	v_add_u32_e32 v173, s26, v173
	v_cmp_lt_i32_e32 vcc, s41, v173
	s_or_b64 s[22:23], vcc, s[22:23]
	v_add_u32_e32 v180, s27, v180
	s_waitcnt vmcnt(21)
	v_pk_add_f32 v[132:133], v[132:133], 1.0 op_sel_hi:[1,0]
	v_pk_add_f32 v[184:185], v[130:131], 1.0 op_sel_hi:[1,0]
	s_waitcnt vmcnt(19)
	v_pk_add_f32 v[186:187], v[136:137], 1.0 op_sel_hi:[1,0]
	v_pk_add_f32 v[188:189], v[134:135], 1.0 op_sel_hi:[1,0]
	s_waitcnt vmcnt(17)
; __device__ __forceinline__ void pass_h_fold(const float* src, const float* g, const float* mod, bf16_t* H, bf16_t* HE, bf16_t* HO) {
;     ...
;             for (int q = 0; q < 2; ++q) { const int s = sb + half * 2 + q, pr = (s == 0) ? SEQ / 2 : SEQ - s;
;                 float t0 = 0.f, t1 = 0.f;
; #pragma unroll
;                 for (int j = 0; j < 4; ++j) { const f32x4 a = v[q][0][j], c = v[q][1][j]; t0 += (a[0] * a[0] + a[1] * a[1]) + (a[2] * a[2] + a[3] * a[3]); t1 += (c[0] * c[0] + c[1] * c[1]) + (c[2] * c[2] + c[3] * c[3]); }
;                 t0 = wave_sum(t0); t1 = wave_sum(t1);
	v_pk_add_f32 v[144:145], v[144:145], 1.0 op_sel_hi:[1,0]
	v_pk_add_f32 v[142:143], v[142:143], 1.0 op_sel_hi:[1,0]
	v_pk_add_f32 v[190:191], v[140:141], 1.0 op_sel_hi:[1,0]
	v_pk_add_f32 v[192:193], v[138:139], 1.0 op_sel_hi:[1,0]
	v_pk_mul_f32 v[130:131], v[2:3], v[132:133]
	v_pk_mul_f32 v[132:133], v[0:1], v[184:185]
	v_pk_mul_f32 v[134:135], v[6:7], v[144:145]
	v_pk_mul_f32 v[136:137], v[4:5], v[142:143]
	v_pk_mul_f32 v[138:139], v[10:11], v[186:187]
	v_pk_mul_f32 v[140:141], v[8:9], v[188:189]
	v_pk_mul_f32 v[142:143], v[14:15], v[190:191]
	v_pk_mul_f32 v[144:145], v[12:13], v[192:193]
	s_waitcnt vmcnt(15)
	v_pk_mul_f32 v[0:1], v[86:87], v[86:87]
	v_pk_mul_f32 v[2:3], v[84:85], v[84:85]
	s_waitcnt vmcnt(14)
	v_pk_mul_f32 v[4:5], v[74:75], v[74:75]
	v_pk_mul_f32 v[6:7], v[72:73], v[72:73]
	s_waitcnt vmcnt(12)
	v_mul_f32_e32 v8, v77, v77
	v_mul_f32_e32 v10, v79, v79
	s_waitcnt vmcnt(11)
	v_pk_mul_f32 v[12:13], v[58:59], v[58:59]
	v_pk_mul_f32 v[14:15], v[56:57], v[56:57]
	v_pk_mov_b32 v[192:193], v[2:3], v[0:1] op_sel:[1,0]
	v_mov_b32_e32 v3, v1
	v_pk_mov_b32 v[196:197], v[6:7], v[4:5] op_sel:[1,0]
	v_mov_b32_e32 v7, v5
	v_mul_f32_e32 v201, v70, v70
	v_mul_f32_e32 v203, v71, v71
	v_pk_fma_f32 v[8:9], v[76:77], v[76:77], v[8:9] op_sel_hi:[1,1,0]
	v_pk_fma_f32 v[10:11], v[78:79], v[78:79], v[10:11] op_sel_hi:[1,1,0]
	v_pk_mov_b32 v[204:205], v[14:15], v[12:13] op_sel:[1,0]
	s_waitcnt vmcnt(10)
	v_pk_mul_f32 v[184:185], v[62:63], v[62:63]
	v_pk_mul_f32 v[186:187], v[60:61], v[60:61]
	s_waitcnt vmcnt(9)
	v_mul_f32_e32 v188, v53, v53
	v_mul_f32_e32 v190, v55, v55
	s_waitcnt vmcnt(8)
	v_mul_f32_e32 v218, v50, v50
	v_mul_f32_e32 v219, v51, v51
	v_mov_b32_e32 v15, v13
	v_pk_mov_b32 v[208:209], v[186:187], v[184:185] op_sel:[1,0]
	v_mov_b32_e32 v187, v185
	v_pk_fma_f32 v[188:189], v[52:53], v[52:53], v[188:189] op_sel_hi:[1,1,0]
	s_waitcnt vmcnt(7)
	v_pk_mul_f32 v[0:1], v[94:95], v[94:95]
	v_pk_mul_f32 v[194:195], v[92:93], v[92:93]
	s_waitcnt vmcnt(6)
	v_pk_mul_f32 v[4:5], v[90:91], v[90:91]
	v_pk_mul_f32 v[198:199], v[88:89], v[88:89]
	s_waitcnt vmcnt(4)
	v_mul_f32_e32 v200, v81, v81
	s_waitcnt vmcnt(3)
	v_pk_mul_f32 v[12:13], v[46:47], v[46:47]
	v_pk_mul_f32 v[206:207], v[44:45], v[44:45]
	s_waitcnt vmcnt(2)
	v_pk_mul_f32 v[184:185], v[42:43], v[42:43]
	v_pk_mul_f32 v[210:211], v[40:41], v[40:41]
	v_pk_fma_f32 v[190:191], v[54:55], v[54:55], v[190:191] op_sel_hi:[1,1,0]
	v_pk_add_f32 v[2:3], v[192:193], v[2:3]
	v_pk_mov_b32 v[192:193], v[194:195], v[0:1] op_sel:[1,0]
	v_mov_b32_e32 v195, v1
	v_pk_add_f32 v[0:1], v[196:197], v[6:7]
	v_pk_mov_b32 v[6:7], v[198:199], v[4:5] op_sel:[1,0]
	v_mov_b32_e32 v199, v5
	v_mul_f32_e32 v213, v68, v68
	v_mul_f32_e32 v215, v69, v69
	v_mul_f32_e32 v202, v83, v83
	v_mov_b32_e32 v9, v201
	v_mov_b32_e32 v11, v203
	v_pk_fma_f32 v[4:5], v[80:81], v[80:81], v[200:201] op_sel_hi:[1,1,0]
	v_pk_add_f32 v[14:15], v[204:205], v[14:15]
	v_pk_mov_b32 v[200:201], v[206:207], v[12:13] op_sel:[1,0]
	v_mov_b32_e32 v207, v13
	v_pk_add_f32 v[12:13], v[208:209], v[186:187]
	v_pk_mov_b32 v[186:187], v[210:211], v[184:185] op_sel:[1,0]
	v_mov_b32_e32 v211, v185
	v_mov_b32_e32 v189, v218
	v_mov_b32_e32 v191, v219
	v_pk_add_f32 v[192:193], v[192:193], v[194:195]
	v_pk_add_f32 v[6:7], v[6:7], v[198:199]
	v_pk_add_f32 v[2:3], v[2:3], v[2:3] op_sel:[0,1] op_sel_hi:[1,0]
	v_pk_add_f32 v[0:1], v[0:1], v[0:1] op_sel:[0,1] op_sel_hi:[1,0]
	v_mul_f32_e32 v216, v48, v48
	v_mul_f32_e32 v217, v49, v49
	v_mul_f32_e32 v220, v64, v64
	v_mul_f32_e32 v221, v65, v65
	v_mul_f32_e32 v222, v66, v66
	v_mul_f32_e32 v223, v67, v67
	v_pk_fma_f32 v[196:197], v[82:83], v[82:83], v[202:203] op_sel_hi:[1,1,0]
	v_pk_add_f32 v[8:9], v[8:9], v[10:11]
	v_pk_add_f32 v[10:11], v[200:201], v[206:207]
	v_pk_add_f32 v[186:187], v[186:187], v[210:211]
	v_pk_add_f32 v[14:15], v[14:15], v[14:15] op_sel:[0,1] op_sel_hi:[1,0]
	v_pk_add_f32 v[12:13], v[12:13], v[12:13] op_sel:[0,1] op_sel_hi:[1,0]
	v_pk_add_f32 v[188:189], v[188:189], v[190:191]
	v_mov_b32_e32 v3, v213
	v_mov_b32_e32 v1, v215
	v_pk_add_f32 v[190:191], v[192:193], v[192:193] op_sel:[0,1] op_sel_hi:[1,0]
	v_pk_add_f32 v[6:7], v[6:7], v[6:7] op_sel:[0,1] op_sel_hi:[1,0]
	s_waitcnt vmcnt(1)
	v_mul_f32_e32 v224, v32, v32
	v_mul_f32_e32 v225, v33, v33
	s_waitcnt vmcnt(0)
	v_mul_f32_e32 v212, v37, v37
	v_mul_f32_e32 v214, v39, v39
	v_mov_b32_e32 v5, v222
	v_mov_b32_e32 v197, v223
	v_mov_b32_e32 v15, v216
	v_mov_b32_e32 v13, v217
	v_pk_add_f32 v[10:11], v[10:11], v[10:11] op_sel:[0,1] op_sel_hi:[1,0]
	v_pk_add_f32 v[186:187], v[186:187], v[186:187] op_sel:[0,1] op_sel_hi:[1,0]
	v_pk_add_f32 v[0:1], v[2:3], v[0:1]
	v_mov_b32_e32 v191, v220
	v_mov_b32_e32 v7, v221
	v_mul_f32_e32 v226, v34, v34
	v_mul_f32_e32 v227, v35, v35
	v_pk_fma_f32 v[184:185], v[36:37], v[36:37], v[212:213] op_sel_hi:[1,1,0]
	v_pk_fma_f32 v[202:203], v[38:39], v[38:39], v[214:215] op_sel_hi:[1,1,0]
	v_pk_add_f32 v[4:5], v[4:5], v[196:197]
	v_pk_add_f32 v[2:3], v[14:15], v[12:13]
	v_mov_b32_e32 v11, v224
	v_mov_b32_e32 v187, v225
	v_pk_add_f32 v[0:1], v[0:1], v[8:9]
	v_pk_add_f32 v[6:7], v[190:191], v[6:7]
	v_mov_b32_e32 v185, v226
	v_mov_b32_e32 v203, v227
	v_pk_add_f32 v[2:3], v[2:3], v[188:189]
	v_pk_add_f32 v[8:9], v[10:11], v[186:187]
	v_add_f32_e32 v10, v0, v1
	v_pk_add_f32 v[0:1], v[6:7], v[4:5]
	v_pk_add_f32 v[184:185], v[184:185], v[202:203]
	v_add_f32_e32 v4, v2, v3
	v_add_f32_e32 v0, v0, v1
	ds_bpermute_b32 v1, v174, v10
	v_pk_add_f32 v[2:3], v[8:9], v[184:185]
	ds_bpermute_b32 v5, v174, v4
	v_add_f32_e32 v2, v2, v3
	ds_bpermute_b32 v3, v174, v0
	ds_bpermute_b32 v6, v174, v2
	s_waitcnt lgkmcnt(3)
	v_add_f32_e32 v1, v10, v1
	s_waitcnt lgkmcnt(2)
; __device__ __forceinline__ void pass_h_fold(const float* src, const float* g, const float* mod, bf16_t* H, bf16_t* HE, bf16_t* HO) {
;     ...
;                 t0 = wave_sum(t0); t1 = wave_sum(t1);
;                 const float r0 = 1.0f / sqrtf(t0 * (1.0f / DM) + EPS), r1 = 1.0f / sqrtf(t1 * (1.0f / DM) + EPS);
;                 u32x2* o0 = (u32x2*)(H + (size_t)(b * SEQ + s) * DM) + lane; u32x2* o1 = (u32x2*)(H + (size_t)(b * SEQ + pr) * DM) + lane;
;                 u32x2* oe = (u32x2*)(HE + (size_t)(b * 1024 + s) * DM) + lane; u32x2* oo = (u32x2*)(HO + (size_t)(b * 1024 + s) * DM) + lane;
; #pragma unroll
;                 for (int j = 0; j < 4; ++j) { const f32x4 h0 = (v[q][0][j] * r0) * mul[j] + sh[j], h1 = (v[q][1][j] * r1) * mul[j] + sh[j];
	v_add_f32_e32 v4, v4, v5
	ds_bpermute_b32 v5, v175, v1
	s_waitcnt lgkmcnt(2)
	v_add_f32_e32 v0, v0, v3
	ds_bpermute_b32 v3, v175, v4
	s_waitcnt lgkmcnt(2)
	v_add_f32_e32 v2, v2, v6
	ds_bpermute_b32 v6, v175, v0
	ds_bpermute_b32 v7, v175, v2
	s_waitcnt lgkmcnt(3)
	v_add_f32_e32 v1, v1, v5
	s_waitcnt lgkmcnt(2)
	v_add_f32_e32 v3, v4, v3
	ds_bpermute_b32 v4, v176, v1
	s_waitcnt lgkmcnt(2)
	v_add_f32_e32 v0, v0, v6
	ds_bpermute_b32 v5, v176, v3
	s_waitcnt lgkmcnt(2)
	v_add_f32_e32 v2, v2, v7
	ds_bpermute_b32 v6, v176, v0
	ds_bpermute_b32 v7, v176, v2
	s_waitcnt lgkmcnt(3)
	v_add_f32_e32 v1, v1, v4
	s_waitcnt lgkmcnt(2)
	v_add_f32_e32 v3, v3, v5
	ds_bpermute_b32 v4, v177, v1
	s_waitcnt lgkmcnt(2)
	v_add_f32_e32 v0, v0, v6
	ds_bpermute_b32 v5, v177, v3
	s_waitcnt lgkmcnt(2)
	v_add_f32_e32 v2, v2, v7
	ds_bpermute_b32 v6, v177, v0
	ds_bpermute_b32 v7, v177, v2
	s_waitcnt lgkmcnt(3)
	v_add_f32_e32 v1, v1, v4
	s_waitcnt lgkmcnt(2)
	v_add_f32_e32 v3, v3, v5
	ds_bpermute_b32 v4, v178, v1
	s_waitcnt lgkmcnt(2)
	v_add_f32_e32 v0, v0, v6
	ds_bpermute_b32 v5, v178, v3
	s_waitcnt lgkmcnt(2)
	v_add_f32_e32 v2, v2, v7
	ds_bpermute_b32 v6, v178, v0
	ds_bpermute_b32 v7, v178, v2
	s_waitcnt lgkmcnt(3)
	v_add_f32_e32 v1, v1, v4
	s_waitcnt lgkmcnt(2)
	v_add_f32_e32 v3, v3, v5
	ds_bpermute_b32 v4, v179, v1
	s_waitcnt lgkmcnt(2)
	v_add_f32_e32 v0, v0, v6
	ds_bpermute_b32 v5, v179, v3
	s_waitcnt lgkmcnt(2)
	v_add_f32_e32 v2, v2, v7
	ds_bpermute_b32 v6, v179, v0
	ds_bpermute_b32 v7, v179, v2
	s_waitcnt lgkmcnt(3)
	v_add_f32_e32 v1, v1, v4
	s_waitcnt lgkmcnt(2)
	v_add_f32_e32 v3, v3, v5
	v_fmamk_f32 v1, v1, 0x3a800000, v182
	s_waitcnt lgkmcnt(1)
	v_add_f32_e32 v0, v0, v6
	v_fmamk_f32 v3, v3, 0x3a800000, v182
	v_mul_f32_e32 v4, 0x4f800000, v1
	v_cmp_gt_f32_e64 s[6:7], s40, v1
	s_waitcnt lgkmcnt(0)
	v_add_f32_e32 v2, v2, v7
	v_fmamk_f32 v0, v0, 0x3a800000, v182
	v_mul_f32_e32 v5, 0x4f800000, v3
	v_cmp_gt_f32_e32 vcc, s40, v3
	v_cndmask_b32_e64 v1, v1, v4, s[6:7]
	v_fmamk_f32 v2, v2, 0x3a800000, v182
	v_mul_f32_e32 v4, 0x4f800000, v0
	v_cmp_gt_f32_e64 s[8:9], s40, v0
	v_cndmask_b32_e32 v3, v3, v5, vcc
	v_sqrt_f32_e32 v6, v1
	v_mul_f32_e32 v5, 0x4f800000, v2
	v_cmp_gt_f32_e64 s[12:13], s40, v2
	v_cndmask_b32_e64 v0, v0, v4, s[8:9]
	v_sqrt_f32_e32 v4, v3
	v_cndmask_b32_e64 v2, v2, v5, s[12:13]
	v_sqrt_f32_e32 v5, v0
	v_sqrt_f32_e32 v7, v2
	v_add_u32_e32 v8, -1, v6
	v_add_u32_e32 v9, 1, v6
	v_add_u32_e32 v10, -1, v4
	v_fma_f32 v12, -v8, v6, v1
	v_add_u32_e32 v11, 1, v4
	v_fma_f32 v13, -v9, v6, v1
	v_add_u32_e32 v14, -1, v5
	v_fma_f32 v184, -v10, v4, v3
	v_cmp_ge_f32_e64 s[14:15], 0, v12
	v_add_u32_e32 v15, 1, v5
	v_fma_f32 v185, -v11, v4, v3
	v_add_u32_e32 v186, -1, v7
	v_cndmask_b32_e64 v6, v6, v8, s[14:15]
	v_fma_f32 v8, -v14, v5, v0
	v_cmp_ge_f32_e64 s[14:15], 0, v184
	v_cmp_lt_f32_e64 s[16:17], 0, v13
	v_add_u32_e32 v187, 1, v7
	v_fma_f32 v12, -v15, v5, v0
	v_cndmask_b32_e64 v4, v4, v10, s[14:15]
	v_cmp_lt_f32_e64 s[14:15], 0, v185
	v_fma_f32 v10, -v186, v7, v2
	v_cndmask_b32_e64 v6, v6, v9, s[16:17]
	v_cmp_ge_f32_e64 s[16:17], 0, v8
	v_fma_f32 v184, -v187, v7, v2
	v_cndmask_b32_e64 v4, v4, v11, s[14:15]
	v_cndmask_b32_e64 v5, v5, v14, s[16:17]
	v_cmp_lt_f32_e64 s[16:17], 0, v12
	v_cmp_ge_f32_e64 s[14:15], 0, v10
	v_mul_f32_e32 v8, 0x37800000, v6
	v_cndmask_b32_e64 v5, v5, v15, s[16:17]
	v_cndmask_b32_e64 v7, v7, v186, s[14:15]
	v_cmp_lt_f32_e64 s[14:15], 0, v184
	v_mul_f32_e32 v9, 0x37800000, v4
	v_cndmask_b32_e64 v6, v6, v8, s[6:7]
	v_cndmask_b32_e64 v7, v7, v187, s[14:15]
	v_mul_f32_e32 v8, 0x37800000, v5
	v_cmp_class_f32_e64 s[6:7], v1, v183
	v_cndmask_b32_e32 v4, v4, v9, vcc
	v_cmp_class_f32_e32 vcc, v3, v183
	v_mul_f32_e32 v9, 0x37800000, v7
	v_cndmask_b32_e64 v1, v6, v1, s[6:7]
	v_cndmask_b32_e64 v5, v5, v8, s[8:9]
	v_cmp_class_f32_e64 s[6:7], v0, v183
	v_cndmask_b32_e32 v184, v4, v3, vcc
	v_cndmask_b32_e64 v3, v7, v9, s[12:13]
	v_cmp_class_f32_e32 vcc, v2, v183
	v_div_scale_f32 v4, s[8:9], v1, v1, 1.0
	v_cndmask_b32_e64 v5, v5, v0, s[6:7]
	v_div_scale_f32 v0, s[6:7], v184, v184, 1.0
	v_cndmask_b32_e32 v185, v3, v2, vcc
	v_rcp_f32_e32 v2, v4
	v_div_scale_f32 v3, s[10:11], v5, v5, 1.0
	v_rcp_f32_e32 v186, v0
	v_div_scale_f32 v9, s[10:11], v185, v185, 1.0
	v_rcp_f32_e32 v11, v3
	v_rcp_f32_e32 v187, v9
	v_fma_f32 v12, -v4, v2, 1.0
	v_div_scale_f32 v6, s[8:9], 1.0, v1, 1.0
	v_fma_f32 v13, -v0, v186, 1.0
	v_fmac_f32_e32 v2, v12, v2
	v_fma_f32 v12, -v3, v11, 1.0
	v_div_scale_f32 v7, s[6:7], 1.0, v184, 1.0
	v_div_scale_f32 v8, s[12:13], 1.0, v5, 1.0
	v_fmac_f32_e32 v186, v13, v186
	v_fma_f32 v13, -v9, v187, 1.0
	v_mul_f32_e32 v14, v6, v2
	v_fmac_f32_e32 v11, v12, v11
	v_mul_f32_e32 v188, v7, v186
	v_fmac_f32_e32 v187, v13, v187
	v_fma_f32 v12, -v4, v14, v6
	v_mul_f32_e32 v13, v8, v11
	v_fma_f32 v15, -v0, v188, v7
	v_fmac_f32_e32 v14, v12, v2
	v_fma_f32 v12, -v3, v13, v8
	v_div_scale_f32 v10, s[14:15], 1.0, v185, 1.0
	v_fmac_f32_e32 v188, v15, v186
	v_fma_f32 v4, -v4, v14, v6
	v_fmac_f32_e32 v13, v12, v11
	s_mov_b64 vcc, s[8:9]
	v_mul_f32_e32 v189, v10, v187
	v_fma_f32 v190, -v0, v188, v7
	v_div_fmas_f32 v0, v4, v2, v14
	v_fma_f32 v2, -v3, v13, v8
	s_mov_b64 vcc, s[12:13]
	v_fma_f32 v15, -v9, v189, v10
	v_div_fixup_f32 v0, v0, v1, 1.0
	v_div_fmas_f32 v1, v2, v11, v13
	v_fmac_f32_e32 v189, v15, v187
	v_div_fixup_f32 v2, v1, v5, 1.0
	s_mov_b64 vcc, s[6:7]
	v_fma_f32 v191, -v9, v189, v10
	v_pk_mul_f32 v[4:5], v[84:85], v[0:1] op_sel_hi:[1,0]
	v_pk_mul_f32 v[6:7], v[86:87], v[0:1] op_sel_hi:[1,0]
	v_pk_mul_f32 v[8:9], v[72:73], v[0:1] op_sel_hi:[1,0]
	v_pk_mul_f32 v[10:11], v[74:75], v[0:1] op_sel_hi:[1,0]
	v_pk_mul_f32 v[12:13], v[76:77], v[0:1] op_sel_hi:[1,0]
; __device__ __forceinline__ unsigned cvt_pk_bf16(float lo, float hi) { unsigned r; asm volatile("v_cvt_pk_bf16_f32 %0, %1, %2" : "=v"(r) : "v"(lo), "v"(hi)); return r; }
; __device__ __forceinline__ void pass_h_fold(const float* src, const float* g, const float* mod, bf16_t* H, bf16_t* HE, bf16_t* HO) {
;     ...
;                 const float r0 = 1.0f / sqrtf(t0 * (1.0f / DM) + EPS), r1 = 1.0f / sqrtf(t1 * (1.0f / DM) + EPS);
;                 u32x2* o0 = (u32x2*)(H + (size_t)(b * SEQ + s) * DM) + lane; u32x2* o1 = (u32x2*)(H + (size_t)(b * SEQ + pr) * DM) + lane;
;                 u32x2* oe = (u32x2*)(HE + (size_t)(b * 1024 + s) * DM) + lane; u32x2* oo = (u32x2*)(HO + (size_t)(b * 1024 + s) * DM) + lane;
; #pragma unroll
;                 for (int j = 0; j < 4; ++j) { const f32x4 h0 = (v[q][0][j] * r0) * mul[j] + sh[j], h1 = (v[q][1][j] * r1) * mul[j] + sh[j];
;                     u32x2 w; w.x = cvt_pk_bf16(h0[0], h0[1]); w.y = cvt_pk_bf16(h0[2], h0[3]); o0[64 * j] = w;
;                     w.x = cvt_pk_bf16(h1[0], h1[1]); w.y = cvt_pk_bf16(h1[2], h1[3]); o1[64 * j] = w;
;                     const f32x4 e = (s == 0) ? h0 : h0 + h1, o = (s == 0) ? (f32x4){0.f, 0.f, 0.f, 0.f} : h0 - h1;
;                     w.x = cvt_pk_bf16(e[0], e[1]); w.y = cvt_pk_bf16(e[2], e[3]); oe[64 * j] = w;
;                     w.x = cvt_pk_bf16(o[0], o[1]); w.y = cvt_pk_bf16(o[2], o[3]); oo[64 * j] = w; } }
	v_pk_mul_f32 v[14:15], v[78:79], v[0:1] op_sel_hi:[1,0]
	v_pk_mul_f32 v[68:69], v[68:69], v[0:1] op_sel_hi:[1,0]
	v_pk_mul_f32 v[0:1], v[70:71], v[0:1] op_sel_hi:[1,0]
	v_div_fmas_f32 v84, v190, v186, v188
	v_pk_mul_f32 v[70:71], v[92:93], v[2:3] op_sel_hi:[1,0]
	s_mov_b64 vcc, s[14:15]
	v_pk_fma_f32 v[4:5], v[132:133], v[4:5], v[28:29]
	v_pk_mul_f32 v[72:73], v[94:95], v[2:3] op_sel_hi:[1,0]
	v_pk_mul_f32 v[74:75], v[88:89], v[2:3] op_sel_hi:[1,0]
	v_pk_mul_f32 v[76:77], v[90:91], v[2:3] op_sel_hi:[1,0]
	v_pk_mul_f32 v[78:79], v[80:81], v[2:3] op_sel_hi:[1,0]
	v_pk_mul_f32 v[80:81], v[82:83], v[2:3] op_sel_hi:[1,0]
	v_pk_mul_f32 v[64:65], v[64:65], v[2:3] op_sel_hi:[1,0]
	v_pk_mul_f32 v[2:3], v[66:67], v[2:3] op_sel_hi:[1,0]
	v_div_fmas_f32 v67, v191, v187, v189
	v_pk_fma_f32 v[70:71], v[132:133], v[70:71], v[28:29]
	v_pk_fma_f32 v[6:7], v[130:131], v[6:7], v[30:31]
	v_div_fixup_f32 v66, v84, v184, 1.0
	v_pk_fma_f32 v[72:73], v[130:131], v[72:73], v[30:31]
	v_cvt_pk_bf16_f32 v82, v4, v5
	v_cvt_pk_bf16_f32 v83, v6, v7
	v_div_fixup_f32 v84, v67, v185, 1.0
	v_sub_f32_e32 v85, v5, v71
	v_pk_fma_f32 v[8:9], v[136:137], v[8:9], v[20:21]
	v_pk_fma_f32 v[74:75], v[136:137], v[74:75], v[20:21]
	v_pk_mul_f32 v[56:57], v[56:57], v[66:67] op_sel_hi:[1,0]
	v_pk_mul_f32 v[58:59], v[58:59], v[66:67] op_sel_hi:[1,0]
	v_pk_mul_f32 v[60:61], v[60:61], v[66:67] op_sel_hi:[1,0]
	v_pk_mul_f32 v[62:63], v[62:63], v[66:67] op_sel_hi:[1,0]
	v_pk_mul_f32 v[52:53], v[52:53], v[66:67] op_sel_hi:[1,0]
	v_pk_mul_f32 v[54:55], v[54:55], v[66:67] op_sel_hi:[1,0]
	v_pk_mul_f32 v[48:49], v[48:49], v[66:67] op_sel_hi:[1,0]
	v_pk_mul_f32 v[50:51], v[50:51], v[66:67] op_sel_hi:[1,0]
	global_store_dwordx2 v[166:167], v[82:83], off sc1
	v_cvt_pk_bf16_f32 v66, v70, v71
	v_cvt_pk_bf16_f32 v67, v72, v73
	v_pk_add_f32 v[82:83], v[4:5], v[70:71]
	v_pk_add_f32 v[86:87], v[6:7], v[72:73]
	v_pk_mul_f32 v[44:45], v[44:45], v[84:85] op_sel_hi:[1,0]
	v_sub_f32_e32 v184, v4, v70
	v_sub_f32_e32 v185, v7, v73
	v_sub_f32_e32 v186, v6, v72
	v_pk_add_f32 v[70:71], v[8:9], v[74:75]
	global_store_dwordx2 v[168:169], v[66:67], off sc1
	v_cndmask_b32_e64 v66, v86, v6, s[4:5]
	v_cndmask_b32_e64 v67, v87, v7, s[4:5]
	v_cndmask_b32_e64 v82, v82, v4, s[4:5]
	v_cndmask_b32_e64 v83, v83, v5, s[4:5]
	v_pk_fma_f32 v[6:7], v[132:133], v[44:45], v[28:29]
	v_cvt_pk_bf16_f32 v44, v82, v83
	v_cvt_pk_bf16_f32 v45, v66, v67
	v_pk_fma_f32 v[10:11], v[134:135], v[10:11], v[22:23]
	v_pk_fma_f32 v[76:77], v[134:135], v[76:77], v[22:23]
	v_sub_f32_e32 v187, v9, v75
	v_sub_f32_e32 v188, v8, v74
	v_cndmask_b32_e64 v186, v186, 0, s[4:5]
	v_cndmask_b32_e64 v185, v185, 0, s[4:5]
	v_cndmask_b32_e64 v184, v184, 0, s[4:5]
	v_cndmask_b32_e64 v199, v85, 0, s[4:5]
	v_cndmask_b32_e64 v202, v70, v8, s[4:5]
	v_cndmask_b32_e64 v203, v71, v9, s[4:5]
	global_store_dwordx2 v[164:165], v[44:45], off sc1
	v_cvt_pk_bf16_f32 v44, v184, v199
	v_cvt_pk_bf16_f32 v45, v186, v185
	global_store_dwordx2 v[162:163], v[44:45], off sc1
	v_cvt_pk_bf16_f32 v8, v8, v9
	v_cvt_pk_bf16_f32 v9, v10, v11
	v_pk_add_f32 v[72:73], v[10:11], v[76:77]
	global_store_dwordx2 v[166:167], v[8:9], off offset:512 sc1
	v_cvt_pk_bf16_f32 v8, v74, v75
	v_cvt_pk_bf16_f32 v9, v76, v77
	v_sub_f32_e32 v189, v11, v77
	v_sub_f32_e32 v190, v10, v76
	v_cndmask_b32_e64 v200, v72, v10, s[4:5]
	v_cndmask_b32_e64 v201, v73, v11, s[4:5]
	global_store_dwordx2 v[168:169], v[8:9], off offset:512 sc1
	v_cvt_pk_bf16_f32 v8, v202, v203
	v_cvt_pk_bf16_f32 v9, v200, v201
	v_cndmask_b32_e64 v190, v190, 0, s[4:5]
	v_cndmask_b32_e64 v189, v189, 0, s[4:5]
	v_cndmask_b32_e64 v188, v188, 0, s[4:5]
	v_cndmask_b32_e64 v187, v187, 0, s[4:5]
	global_store_dwordx2 v[164:165], v[8:9], off offset:512 sc1
	v_cvt_pk_bf16_f32 v8, v188, v187
	v_cvt_pk_bf16_f32 v9, v190, v189
	v_pk_fma_f32 v[14:15], v[138:139], v[14:15], v[18:19]
	v_pk_fma_f32 v[12:13], v[140:141], v[12:13], v[16:17]
	v_pk_fma_f32 v[80:81], v[138:139], v[80:81], v[18:19]
	v_pk_fma_f32 v[78:79], v[140:141], v[78:79], v[16:17]
	global_store_dwordx2 v[162:163], v[8:9], off offset:512 sc1
	v_cvt_pk_bf16_f32 v8, v12, v13
	v_cvt_pk_bf16_f32 v9, v14, v15
	v_pk_add_f32 v[88:89], v[12:13], v[78:79]
	v_pk_add_f32 v[90:91], v[14:15], v[80:81]
	global_store_dwordx2 v[166:167], v[8:9], off offset:1024 sc1
	v_cvt_pk_bf16_f32 v8, v78, v79
	v_cvt_pk_bf16_f32 v9, v80, v81
	v_pk_fma_f32 v[0:1], v[142:143], v[0:1], v[26:27]
	v_pk_fma_f32 v[2:3], v[142:143], v[2:3], v[26:27]
	v_sub_f32_e32 v191, v13, v79
	v_sub_f32_e32 v192, v12, v78
	v_sub_f32_e32 v193, v15, v81
	v_sub_f32_e32 v194, v14, v80
	v_cndmask_b32_e64 v90, v90, v14, s[4:5]
	v_cndmask_b32_e64 v91, v91, v15, s[4:5]
	v_cndmask_b32_e64 v204, v88, v12, s[4:5]
	v_cndmask_b32_e64 v205, v89, v13, s[4:5]
	global_store_dwordx2 v[168:169], v[8:9], off offset:1024 sc1
	v_cvt_pk_bf16_f32 v8, v204, v205
	v_cvt_pk_bf16_f32 v9, v90, v91
	v_pk_fma_f32 v[68:69], v[144:145], v[68:69], v[24:25]
	v_pk_fma_f32 v[64:65], v[144:145], v[64:65], v[24:25]
	v_pk_add_f32 v[94:95], v[0:1], v[2:3]
	v_cndmask_b32_e64 v194, v194, 0, s[4:5]
	v_cndmask_b32_e64 v193, v193, 0, s[4:5]
	v_cndmask_b32_e64 v192, v192, 0, s[4:5]
	v_cndmask_b32_e64 v191, v191, 0, s[4:5]
	global_store_dwordx2 v[164:165], v[8:9], off offset:1024 sc1
	v_cvt_pk_bf16_f32 v8, v192, v191
	v_cvt_pk_bf16_f32 v9, v194, v193
	v_pk_add_f32 v[92:93], v[68:69], v[64:65]
	v_sub_f32_e32 v197, v1, v3
	v_sub_f32_e32 v198, v0, v2
	v_cndmask_b32_e64 v94, v94, v0, s[4:5]
	v_cndmask_b32_e64 v95, v95, v1, s[4:5]
	global_store_dwordx2 v[162:163], v[8:9], off offset:1024 sc1
	v_cvt_pk_bf16_f32 v8, v68, v69
	v_cvt_pk_bf16_f32 v9, v0, v1
	global_store_dwordx2 v[166:167], v[8:9], off offset:1536 sc1
; __device__ __forceinline__ unsigned cvt_pk_bf16(float lo, float hi) { unsigned r; asm volatile("v_cvt_pk_bf16_f32 %0, %1, %2" : "=v"(r) : "v"(lo), "v"(hi)); return r; }
; __device__ __forceinline__ void pass_h_fold(const float* src, const float* g, const float* mod, bf16_t* H, bf16_t* HE, bf16_t* HO) {
;     ...
;         for (int half = 0; half < 2; ++half) {
;             f32x4 v[2][2][4];
; #pragma unroll
;             for (int q = 0; q < 2; ++q) { const int s = sb + half * 2 + q, pr = (s == 0) ? SEQ / 2 : SEQ - s;
;                 const f32x4* x0 = (const f32x4*)(src + (size_t)(b * SEQ + s) * DM) + lane; const f32x4* x1 = (const f32x4*)(src + (size_t)(b * SEQ + pr) * DM) + lane;
; #pragma unroll
;                 for (int j = 0; j < 4; ++j) { v[q][0][j] = x0[64 * j]; v[q][1][j] = x1[64 * j]; } }
;     ...
;                 const float r0 = 1.0f / sqrtf(t0 * (1.0f / DM) + EPS), r1 = 1.0f / sqrtf(t1 * (1.0f / DM) + EPS);
;                 u32x2* o0 = (u32x2*)(H + (size_t)(b * SEQ + s) * DM) + lane; u32x2* o1 = (u32x2*)(H + (size_t)(b * SEQ + pr) * DM) + lane;
;                 u32x2* oe = (u32x2*)(HE + (size_t)(b * 1024 + s) * DM) + lane; u32x2* oo = (u32x2*)(HO + (size_t)(b * 1024 + s) * DM) + lane;
; #pragma unroll
;                 for (int j = 0; j < 4; ++j) { const f32x4 h0 = (v[q][0][j] * r0) * mul[j] + sh[j], h1 = (v[q][1][j] * r1) * mul[j] + sh[j];
;                     u32x2 w; w.x = cvt_pk_bf16(h0[0], h0[1]); w.y = cvt_pk_bf16(h0[2], h0[3]); o0[64 * j] = w;
;                     w.x = cvt_pk_bf16(h1[0], h1[1]); w.y = cvt_pk_bf16(h1[2], h1[3]); o1[64 * j] = w;
;                     const f32x4 e = (s == 0) ? h0 : h0 + h1, o = (s == 0) ? (f32x4){0.f, 0.f, 0.f, 0.f} : h0 - h1;
;                     w.x = cvt_pk_bf16(e[0], e[1]); w.y = cvt_pk_bf16(e[2], e[3]); oe[64 * j] = w;
;                     w.x = cvt_pk_bf16(o[0], o[1]); w.y = cvt_pk_bf16(o[2], o[3]); oo[64 * j] = w; } }
	v_cvt_pk_bf16_f32 v0, v64, v65
	v_cvt_pk_bf16_f32 v1, v2, v3
	v_sub_f32_e32 v195, v69, v65
	v_sub_f32_e32 v196, v68, v64
	v_cndmask_b32_e64 v92, v92, v68, s[4:5]
	v_cndmask_b32_e64 v93, v93, v69, s[4:5]
	global_store_dwordx2 v[168:169], v[0:1], off offset:1536 sc1
	v_cvt_pk_bf16_f32 v0, v92, v93
	v_cvt_pk_bf16_f32 v1, v94, v95
	v_cndmask_b32_e64 v198, v198, 0, s[4:5]
	v_cndmask_b32_e64 v197, v197, 0, s[4:5]
	v_cndmask_b32_e64 v196, v196, 0, s[4:5]
	v_cndmask_b32_e64 v195, v195, 0, s[4:5]
	global_store_dwordx2 v[164:165], v[0:1], off offset:1536 sc1
	v_cvt_pk_bf16_f32 v0, v196, v195
	v_cvt_pk_bf16_f32 v1, v198, v197
	v_pk_fma_f32 v[58:59], v[130:131], v[58:59], v[30:31]
	v_pk_fma_f32 v[56:57], v[132:133], v[56:57], v[28:29]
	v_pk_mul_f32 v[46:47], v[46:47], v[84:85] op_sel_hi:[1,0]
	global_store_dwordx2 v[162:163], v[0:1], off offset:1536 sc1
	v_cvt_pk_bf16_f32 v0, v56, v57
	v_cvt_pk_bf16_f32 v1, v58, v59
	v_pk_fma_f32 v[4:5], v[130:131], v[46:47], v[30:31]
	global_store_dwordx2 v[154:155], v[0:1], off sc1
	v_cvt_pk_bf16_f32 v0, v6, v7
	v_cvt_pk_bf16_f32 v1, v4, v5
	v_pk_add_f32 v[46:47], v[58:59], v[4:5]
	v_pk_add_f32 v[66:67], v[56:57], v[6:7]
	global_store_dwordx2 v[160:161], v[0:1], off sc1
	v_cvt_pk_bf16_f32 v0, v66, v67
	v_cvt_pk_bf16_f32 v1, v46, v47
	v_sub_f32_e32 v206, v58, v4
	v_sub_f32_e32 v207, v59, v5
	v_sub_f32_e32 v208, v56, v6
	v_sub_f32_e32 v209, v57, v7
	global_store_dwordx2 v[152:153], v[0:1], off sc1
	v_cvt_pk_bf16_f32 v0, v208, v209
	v_cvt_pk_bf16_f32 v1, v206, v207
	v_pk_fma_f32 v[62:63], v[134:135], v[62:63], v[22:23]
	v_pk_fma_f32 v[60:61], v[136:137], v[60:61], v[20:21]
	v_pk_mul_f32 v[40:41], v[40:41], v[84:85] op_sel_hi:[1,0]
	v_pk_mul_f32 v[42:43], v[42:43], v[84:85] op_sel_hi:[1,0]
	global_store_dwordx2 v[150:151], v[0:1], off sc1
	v_cvt_pk_bf16_f32 v0, v60, v61
	v_cvt_pk_bf16_f32 v1, v62, v63
	v_pk_fma_f32 v[42:43], v[134:135], v[42:43], v[22:23]
	v_pk_fma_f32 v[40:41], v[136:137], v[40:41], v[20:21]
	global_store_dwordx2 v[154:155], v[0:1], off offset:512 sc1
	v_cvt_pk_bf16_f32 v0, v40, v41
	v_cvt_pk_bf16_f32 v1, v42, v43
	v_pk_add_f32 v[70:71], v[62:63], v[42:43]
	v_pk_add_f32 v[72:73], v[60:61], v[40:41]
	global_store_dwordx2 v[160:161], v[0:1], off offset:512 sc1
	v_cvt_pk_bf16_f32 v0, v72, v73
	v_cvt_pk_bf16_f32 v1, v70, v71
	v_sub_f32_e32 v210, v62, v42
	v_sub_f32_e32 v211, v63, v43
	v_sub_f32_e32 v212, v60, v40
	v_sub_f32_e32 v213, v61, v41
	global_store_dwordx2 v[152:153], v[0:1], off offset:512 sc1
	v_cvt_pk_bf16_f32 v0, v212, v213
	v_cvt_pk_bf16_f32 v1, v210, v211
	v_pk_fma_f32 v[54:55], v[138:139], v[54:55], v[18:19]
	v_pk_fma_f32 v[52:53], v[140:141], v[52:53], v[16:17]
	v_pk_mul_f32 v[36:37], v[36:37], v[84:85] op_sel_hi:[1,0]
	v_pk_mul_f32 v[38:39], v[38:39], v[84:85] op_sel_hi:[1,0]
	global_store_dwordx2 v[150:151], v[0:1], off offset:512 sc1
	v_cvt_pk_bf16_f32 v0, v52, v53
	v_cvt_pk_bf16_f32 v1, v54, v55
	v_pk_fma_f32 v[38:39], v[138:139], v[38:39], v[18:19]
	v_pk_fma_f32 v[36:37], v[140:141], v[36:37], v[16:17]
	global_store_dwordx2 v[154:155], v[0:1], off offset:1024 sc1
	v_cvt_pk_bf16_f32 v0, v36, v37
	v_cvt_pk_bf16_f32 v1, v38, v39
	v_pk_mul_f32 v[32:33], v[32:33], v[84:85] op_sel_hi:[1,0]
	v_pk_mul_f32 v[34:35], v[34:35], v[84:85] op_sel_hi:[1,0]
	v_pk_add_f32 v[82:83], v[54:55], v[38:39]
	v_pk_add_f32 v[84:85], v[52:53], v[36:37]
	global_store_dwordx2 v[160:161], v[0:1], off offset:1024 sc1
	v_cvt_pk_bf16_f32 v0, v84, v85
	v_cvt_pk_bf16_f32 v1, v82, v83
	v_sub_f32_e32 v214, v54, v38
	v_sub_f32_e32 v215, v55, v39
	v_sub_f32_e32 v216, v52, v36
	v_sub_f32_e32 v217, v53, v37
	global_store_dwordx2 v[152:153], v[0:1], off offset:1024 sc1
	v_cvt_pk_bf16_f32 v0, v216, v217
	v_cvt_pk_bf16_f32 v1, v214, v215
	v_pk_fma_f32 v[50:51], v[142:143], v[50:51], v[26:27]
	v_pk_fma_f32 v[48:49], v[144:145], v[48:49], v[24:25]
	global_store_dwordx2 v[150:151], v[0:1], off offset:1024 sc1
	v_cvt_pk_bf16_f32 v0, v48, v49
	v_cvt_pk_bf16_f32 v1, v50, v51
	v_pk_fma_f32 v[34:35], v[142:143], v[34:35], v[26:27]
	v_pk_fma_f32 v[32:33], v[144:145], v[32:33], v[24:25]
	global_store_dwordx2 v[154:155], v[0:1], off offset:1536 sc1
	v_cvt_pk_bf16_f32 v0, v32, v33
	v_cvt_pk_bf16_f32 v1, v34, v35
	v_pk_add_f32 v[86:87], v[50:51], v[34:35]
	v_pk_add_f32 v[88:89], v[48:49], v[32:33]
	global_store_dwordx2 v[160:161], v[0:1], off offset:1536 sc1
	v_cvt_pk_bf16_f32 v0, v88, v89
	v_cvt_pk_bf16_f32 v1, v86, v87
	v_sub_f32_e32 v218, v50, v34
	v_sub_f32_e32 v219, v51, v35
	v_sub_f32_e32 v220, v48, v32
	v_sub_f32_e32 v221, v49, v33
	global_store_dwordx2 v[152:153], v[0:1], off offset:1536 sc1
	v_cvt_pk_bf16_f32 v0, v220, v221
	v_cvt_pk_bf16_f32 v1, v218, v219
	global_store_dwordx2 v[150:151], v[0:1], off offset:1536 sc1
	global_load_dwordx4 v[68:71], v[148:149], off nt
	global_load_dwordx4 v[60:63], v[158:159], off nt
	global_load_dwordx4 v[72:75], v[148:149], off offset:1024 nt
	global_load_dwordx4 v[52:55], v[158:159], off offset:1024 nt
	global_load_dwordx4 v[64:67], v[148:149], off offset:3072 nt
	global_load_dwordx4 v[76:79], v[148:149], off offset:2048 nt
	global_load_dwordx4 v[48:51], v[158:159], off offset:3072 nt
	global_load_dwordx4 v[56:59], v[158:159], off offset:2048 nt
	global_load_dwordx4 v[32:35], v[146:147], off nt
	global_load_dwordx4 v[4:7], v[156:157], off nt
	global_load_dwordx4 v[40:43], v[146:147], off offset:1024 nt
	global_load_dwordx4 v[8:11], v[156:157], off offset:1024 nt
	global_load_dwordx4 v[36:39], v[146:147], off offset:3072 nt
	global_load_dwordx4 v[44:47], v[146:147], off offset:2048 nt
	global_load_dwordx4 v[0:3], v[156:157], off offset:3072 nt
	global_load_dwordx4 v[12:15], v[156:157], off offset:2048 nt
	s_waitcnt vmcnt(15)
; __device__ __forceinline__ void pass_h_fold(const float* src, const float* g, const float* mod, bf16_t* H, bf16_t* HE, bf16_t* HO) {
;     ...
;             for (int q = 0; q < 2; ++q) { const int s = sb + half * 2 + q, pr = (s == 0) ? SEQ / 2 : SEQ - s;
;                 float t0 = 0.f, t1 = 0.f;
; #pragma unroll
;                 for (int j = 0; j < 4; ++j) { const f32x4 a = v[q][0][j], c = v[q][1][j]; t0 += (a[0] * a[0] + a[1] * a[1]) + (a[2] * a[2] + a[3] * a[3]); t1 += (c[0] * c[0] + c[1] * c[1]) + (c[2] * c[2] + c[3] * c[3]); }
;                 t0 = wave_sum(t0); t1 = wave_sum(t1);
	v_pk_mul_f32 v[80:81], v[70:71], v[70:71]
	v_pk_mul_f32 v[82:83], v[68:69], v[68:69]
	s_waitcnt vmcnt(14)
	v_pk_mul_f32 v[84:85], v[62:63], v[62:63]
	v_pk_mul_f32 v[86:87], v[60:61], v[60:61]
	s_waitcnt vmcnt(13)
	v_pk_mul_f32 v[88:89], v[74:75], v[74:75]
	v_pk_mul_f32 v[90:91], v[72:73], v[72:73]
	s_waitcnt vmcnt(12)
	v_pk_mul_f32 v[92:93], v[54:55], v[54:55]
	v_pk_mul_f32 v[94:95], v[52:53], v[52:53]
	s_waitcnt vmcnt(10)
	v_mul_f32_e32 v146, v77, v77
	v_mul_f32_e32 v148, v79, v79
	s_waitcnt vmcnt(8)
	v_mul_f32_e32 v150, v57, v57
	v_mul_f32_e32 v152, v59, v59
	s_waitcnt vmcnt(7)
	v_pk_mul_f32 v[154:155], v[34:35], v[34:35]
	v_pk_mul_f32 v[156:157], v[32:33], v[32:33]
	s_waitcnt vmcnt(6)
	v_pk_mul_f32 v[158:159], v[6:7], v[6:7]
	v_pk_mul_f32 v[160:161], v[4:5], v[4:5]
	s_waitcnt vmcnt(5)
	v_pk_mul_f32 v[162:163], v[42:43], v[42:43]
	v_pk_mul_f32 v[164:165], v[40:41], v[40:41]
	v_pk_mov_b32 v[192:193], v[82:83], v[80:81] op_sel:[1,0]
	v_mov_b32_e32 v83, v81
	v_pk_mov_b32 v[80:81], v[86:87], v[84:85] op_sel:[1,0]
	v_mov_b32_e32 v87, v85
	v_pk_mov_b32 v[84:85], v[90:91], v[88:89] op_sel:[1,0]
	v_mov_b32_e32 v91, v89
	s_waitcnt vmcnt(4)
	v_pk_mul_f32 v[166:167], v[10:11], v[10:11]
	v_pk_mul_f32 v[168:169], v[8:9], v[8:9]
	v_pk_mov_b32 v[88:89], v[94:95], v[92:93] op_sel:[1,0]
	v_mov_b32_e32 v95, v93
	v_pk_fma_f32 v[92:93], v[76:77], v[76:77], v[146:147] op_sel_hi:[1,1,0]
	v_pk_fma_f32 v[146:147], v[78:79], v[78:79], v[148:149] op_sel_hi:[1,1,0]
	v_pk_fma_f32 v[148:149], v[56:57], v[56:57], v[150:151] op_sel_hi:[1,1,0]
	v_pk_fma_f32 v[150:151], v[58:59], v[58:59], v[152:153] op_sel_hi:[1,1,0]
	v_pk_mov_b32 v[152:153], v[156:157], v[154:155] op_sel:[1,0]
	v_mov_b32_e32 v157, v155
	v_pk_mov_b32 v[154:155], v[160:161], v[158:159] op_sel:[1,0]
	v_mov_b32_e32 v161, v159
	v_pk_mov_b32 v[158:159], v[164:165], v[162:163] op_sel:[1,0]
	v_mov_b32_e32 v165, v163
	v_pk_add_f32 v[82:83], v[192:193], v[82:83]
	v_pk_add_f32 v[84:85], v[84:85], v[90:91]
	v_mul_f32_e32 v191, v64, v64
	v_mul_f32_e32 v194, v65, v65
	v_mul_f32_e32 v195, v66, v66
	v_mul_f32_e32 v196, v67, v67
	v_mul_f32_e32 v199, v50, v50
	v_mul_f32_e32 v200, v51, v51
	s_waitcnt vmcnt(2)
	v_mul_f32_e32 v184, v45, v45
	v_mul_f32_e32 v186, v47, v47
	v_pk_mov_b32 v[162:163], v[168:169], v[166:167] op_sel:[1,0]
	v_mov_b32_e32 v169, v167
	v_pk_add_f32 v[80:81], v[80:81], v[86:87]
	v_pk_add_f32 v[86:87], v[88:89], v[94:95]
	v_pk_add_f32 v[88:89], v[152:153], v[156:157]
	v_pk_add_f32 v[94:95], v[158:159], v[164:165]
	v_pk_add_f32 v[82:83], v[82:83], v[82:83] op_sel:[0,1] op_sel_hi:[1,0]
	v_pk_add_f32 v[84:85], v[84:85], v[84:85] op_sel:[0,1] op_sel_hi:[1,0]
	v_mul_f32_e32 v197, v48, v48
	v_mul_f32_e32 v198, v49, v49
	v_mul_f32_e32 v201, v36, v36
	v_mul_f32_e32 v202, v37, v37
	v_mul_f32_e32 v203, v38, v38
	v_mul_f32_e32 v204, v39, v39
	s_waitcnt vmcnt(0)
	v_mul_f32_e32 v188, v13, v13
	v_mul_f32_e32 v190, v15, v15
	v_pk_fma_f32 v[166:167], v[44:45], v[44:45], v[184:185] op_sel_hi:[1,1,0]
	v_pk_fma_f32 v[184:185], v[46:47], v[46:47], v[186:187] op_sel_hi:[1,1,0]
	v_mov_b32_e32 v93, v195
	v_mov_b32_e32 v147, v196
	v_mov_b32_e32 v149, v199
	v_mov_b32_e32 v151, v200
	v_pk_add_f32 v[90:91], v[154:155], v[160:161]
	v_pk_add_f32 v[152:153], v[162:163], v[168:169]
	v_pk_add_f32 v[80:81], v[80:81], v[80:81] op_sel:[0,1] op_sel_hi:[1,0]
	v_pk_add_f32 v[86:87], v[86:87], v[86:87] op_sel:[0,1] op_sel_hi:[1,0]
	v_pk_add_f32 v[88:89], v[88:89], v[88:89] op_sel:[0,1] op_sel_hi:[1,0]
	v_pk_add_f32 v[94:95], v[94:95], v[94:95] op_sel:[0,1] op_sel_hi:[1,0]
	v_mov_b32_e32 v83, v191
	v_mov_b32_e32 v85, v194
	v_mul_f32_e32 v205, v0, v0
	v_mul_f32_e32 v206, v1, v1
	v_mul_f32_e32 v207, v2, v2
	v_mul_f32_e32 v208, v3, v3
	v_pk_fma_f32 v[186:187], v[12:13], v[12:13], v[188:189] op_sel_hi:[1,1,0]
	v_pk_fma_f32 v[188:189], v[14:15], v[14:15], v[190:191] op_sel_hi:[1,1,0]
	v_mov_b32_e32 v167, v203
	v_mov_b32_e32 v185, v204
	v_pk_add_f32 v[92:93], v[92:93], v[146:147]
	v_pk_add_f32 v[146:147], v[148:149], v[150:151]
	v_pk_add_f32 v[90:91], v[90:91], v[90:91] op_sel:[0,1] op_sel_hi:[1,0]
	v_pk_add_f32 v[150:151], v[152:153], v[152:153] op_sel:[0,1] op_sel_hi:[1,0]
	v_mov_b32_e32 v81, v197
	v_mov_b32_e32 v87, v198
	v_mov_b32_e32 v89, v201
	v_mov_b32_e32 v95, v202
	v_pk_add_f32 v[82:83], v[82:83], v[84:85]
	v_mov_b32_e32 v187, v207
	v_mov_b32_e32 v189, v208
	v_pk_add_f32 v[148:149], v[166:167], v[184:185]
	v_mov_b32_e32 v91, v205
	v_mov_b32_e32 v151, v206
	v_pk_add_f32 v[80:81], v[80:81], v[86:87]
	v_pk_add_f32 v[84:85], v[88:89], v[94:95]
	v_pk_add_f32 v[82:83], v[82:83], v[92:93]
	v_pk_add_f32 v[152:153], v[186:187], v[188:189]
	v_pk_add_f32 v[86:87], v[90:91], v[150:151]
	v_pk_add_f32 v[80:81], v[80:81], v[146:147]
	v_pk_add_f32 v[84:85], v[84:85], v[148:149]
	v_add_f32_e32 v82, v82, v83
	v_pk_add_f32 v[86:87], v[86:87], v[152:153]
	v_add_f32_e32 v80, v80, v81
	v_add_f32_e32 v81, v84, v85
	ds_bpermute_b32 v84, v174, v82
	v_add_f32_e32 v83, v86, v87
	ds_bpermute_b32 v85, v174, v80
	ds_bpermute_b32 v86, v174, v81
	ds_bpermute_b32 v87, v174, v83
	s_waitcnt lgkmcnt(3)
	v_add_f32_e32 v82, v82, v84
	ds_bpermute_b32 v84, v175, v82
	s_waitcnt lgkmcnt(3)
	v_add_f32_e32 v80, v80, v85
	s_waitcnt lgkmcnt(2)
	v_add_f32_e32 v81, v81, v86
	ds_bpermute_b32 v85, v175, v80
	ds_bpermute_b32 v86, v175, v81
	s_waitcnt lgkmcnt(3)
	v_add_f32_e32 v83, v83, v87
	ds_bpermute_b32 v87, v175, v83
	s_waitcnt lgkmcnt(3)
	v_add_f32_e32 v82, v82, v84
	s_waitcnt lgkmcnt(2)
	v_add_f32_e32 v80, v80, v85
	s_waitcnt lgkmcnt(1)
	v_add_f32_e32 v81, v81, v86
	ds_bpermute_b32 v84, v176, v82
	ds_bpermute_b32 v85, v176, v80
	ds_bpermute_b32 v86, v176, v81
	s_waitcnt lgkmcnt(3)
; __device__ __forceinline__ void pass_h_fold(const float* src, const float* g, const float* mod, bf16_t* H, bf16_t* HE, bf16_t* HO) {
;     ...
;                 t0 = wave_sum(t0); t1 = wave_sum(t1);
;                 const float r0 = 1.0f / sqrtf(t0 * (1.0f / DM) + EPS), r1 = 1.0f / sqrtf(t1 * (1.0f / DM) + EPS);
;                 u32x2* o0 = (u32x2*)(H + (size_t)(b * SEQ + s) * DM) + lane; u32x2* o1 = (u32x2*)(H + (size_t)(b * SEQ + pr) * DM) + lane;
;                 u32x2* oe = (u32x2*)(HE + (size_t)(b * 1024 + s) * DM) + lane; u32x2* oo = (u32x2*)(HO + (size_t)(b * 1024 + s) * DM) + lane;
; #pragma unroll
;                 for (int j = 0; j < 4; ++j) { const f32x4 h0 = (v[q][0][j] * r0) * mul[j] + sh[j], h1 = (v[q][1][j] * r1) * mul[j] + sh[j];
	v_add_f32_e32 v83, v83, v87
	ds_bpermute_b32 v87, v176, v83
	s_waitcnt lgkmcnt(3)
	v_add_f32_e32 v82, v82, v84
	s_waitcnt lgkmcnt(2)
	v_add_f32_e32 v80, v80, v85
	s_waitcnt lgkmcnt(1)
	v_add_f32_e32 v81, v81, v86
	ds_bpermute_b32 v84, v177, v82
	ds_bpermute_b32 v85, v177, v80
	ds_bpermute_b32 v86, v177, v81
	s_waitcnt lgkmcnt(3)
	v_add_f32_e32 v83, v83, v87
	ds_bpermute_b32 v87, v177, v83
	s_waitcnt lgkmcnt(3)
	v_add_f32_e32 v82, v82, v84
	s_waitcnt lgkmcnt(2)
	v_add_f32_e32 v80, v80, v85
	s_waitcnt lgkmcnt(1)
	v_add_f32_e32 v81, v81, v86
	ds_bpermute_b32 v84, v178, v82
	ds_bpermute_b32 v85, v178, v80
	ds_bpermute_b32 v86, v178, v81
	s_waitcnt lgkmcnt(3)
	v_add_f32_e32 v83, v83, v87
	ds_bpermute_b32 v87, v178, v83
	s_waitcnt lgkmcnt(3)
	v_add_f32_e32 v82, v82, v84
	s_waitcnt lgkmcnt(2)
	v_add_f32_e32 v80, v80, v85
	s_waitcnt lgkmcnt(1)
	v_add_f32_e32 v81, v81, v86
	ds_bpermute_b32 v84, v179, v82
	ds_bpermute_b32 v85, v179, v80
	ds_bpermute_b32 v86, v179, v81
	s_waitcnt lgkmcnt(3)
	v_add_f32_e32 v83, v83, v87
	ds_bpermute_b32 v87, v179, v83
	s_waitcnt lgkmcnt(3)
	v_add_f32_e32 v82, v82, v84
	s_waitcnt lgkmcnt(2)
	v_add_f32_e32 v80, v80, v85
	s_waitcnt lgkmcnt(1)
	v_add_f32_e32 v81, v81, v86
	v_fmamk_f32 v82, v82, 0x3a800000, v182
	v_fmamk_f32 v80, v80, 0x3a800000, v182
	v_fmamk_f32 v81, v81, 0x3a800000, v182
	v_mul_f32_e32 v84, 0x4f800000, v82
	v_cmp_gt_f32_e64 s[8:9], s40, v82
	v_mul_f32_e32 v85, 0x4f800000, v80
	v_cmp_gt_f32_e32 vcc, s40, v80
	v_mul_f32_e32 v86, 0x4f800000, v81
	v_cmp_gt_f32_e64 s[4:5], s40, v81
	v_cndmask_b32_e64 v82, v82, v84, s[8:9]
	s_waitcnt lgkmcnt(0)
	v_add_f32_e32 v83, v83, v87
	v_cndmask_b32_e32 v80, v80, v85, vcc
	v_cndmask_b32_e64 v81, v81, v86, s[4:5]
	v_sqrt_f32_e32 v84, v82
	v_fmamk_f32 v83, v83, 0x3a800000, v182
	v_sqrt_f32_e32 v85, v80
	v_sqrt_f32_e32 v86, v81
	v_mul_f32_e32 v87, 0x4f800000, v83
	v_cmp_gt_f32_e64 s[6:7], s40, v83
	v_add_u32_e32 v88, -1, v84
	v_add_u32_e32 v89, 1, v84
	v_cndmask_b32_e64 v83, v83, v87, s[6:7]
	v_sqrt_f32_e32 v87, v83
	v_add_u32_e32 v90, -1, v85
	v_add_u32_e32 v92, -1, v86
	v_fma_f32 v146, -v88, v84, v82
	v_add_u32_e32 v91, 1, v85
	v_add_u32_e32 v93, 1, v86
	v_fma_f32 v147, -v89, v84, v82
	v_fma_f32 v148, -v90, v85, v80
	v_fma_f32 v150, -v92, v86, v81
	v_cmp_ge_f32_e64 s[12:13], 0, v146
	v_fma_f32 v149, -v91, v85, v80
	v_fma_f32 v151, -v93, v86, v81
	v_cndmask_b32_e64 v84, v84, v88, s[12:13]
	v_cmp_ge_f32_e64 s[12:13], 0, v148
	v_cmp_ge_f32_e64 s[14:15], 0, v150
	v_cmp_lt_f32_e64 s[18:19], 0, v147
	v_add_u32_e32 v94, -1, v87
	v_cndmask_b32_e64 v85, v85, v90, s[12:13]
	v_cmp_lt_f32_e64 s[12:13], 0, v149
	v_cndmask_b32_e64 v86, v86, v92, s[14:15]
	v_cmp_lt_f32_e64 s[14:15], 0, v151
	v_cndmask_b32_e64 v84, v84, v89, s[18:19]
	v_add_u32_e32 v95, 1, v87
	v_fma_f32 v152, -v94, v87, v83
	v_cndmask_b32_e64 v85, v85, v91, s[12:13]
	v_cndmask_b32_e64 v86, v86, v93, s[14:15]
	v_mul_f32_e32 v88, 0x37800000, v84
	v_fma_f32 v153, -v95, v87, v83
	v_cmp_ge_f32_e64 s[16:17], 0, v152
	v_mul_f32_e32 v89, 0x37800000, v85
	v_mul_f32_e32 v90, 0x37800000, v86
	v_cndmask_b32_e64 v84, v84, v88, s[8:9]
	v_cmp_class_f32_e64 s[8:9], v82, v183
	v_cndmask_b32_e64 v87, v87, v94, s[16:17]
	v_cmp_lt_f32_e64 s[16:17], 0, v153
	v_cndmask_b32_e32 v85, v85, v89, vcc
	v_cmp_class_f32_e32 vcc, v80, v183
	v_cndmask_b32_e64 v86, v86, v90, s[4:5]
	v_cmp_class_f32_e64 s[4:5], v81, v183
	v_cndmask_b32_e64 v82, v84, v82, s[8:9]
	v_cndmask_b32_e64 v87, v87, v95, s[16:17]
	v_cndmask_b32_e32 v84, v85, v80, vcc
	v_cndmask_b32_e64 v81, v86, v81, s[4:5]
	v_div_scale_f32 v80, s[4:5], v82, v82, 1.0
	v_mul_f32_e32 v91, 0x37800000, v87
	v_div_scale_f32 v86, s[4:5], v84, v84, 1.0
	v_rcp_f32_e32 v92, v80
	v_cndmask_b32_e64 v87, v87, v91, s[6:7]
	v_cmp_class_f32_e64 s[6:7], v83, v183
	v_rcp_f32_e32 v93, v86
	v_fma_f32 v146, -v80, v92, 1.0
	v_cndmask_b32_e64 v85, v87, v83, s[6:7]
	v_div_scale_f32 v88, s[6:7], v81, v81, 1.0
	v_div_scale_f32 v90, s[8:9], v85, v85, 1.0
	v_rcp_f32_e32 v94, v88
	v_rcp_f32_e32 v95, v90
	v_div_scale_f32 v83, vcc, 1.0, v82, 1.0
	v_fma_f32 v147, -v86, v93, 1.0
	v_fmac_f32_e32 v92, v146, v92
	v_div_scale_f32 v87, s[4:5], 1.0, v84, 1.0
	v_fmac_f32_e32 v93, v147, v93
	v_mul_f32_e32 v146, v83, v92
	v_fma_f32 v148, -v88, v94, 1.0
	v_mul_f32_e32 v147, v87, v93
	v_fma_f32 v150, -v80, v146, v83
	v_div_scale_f32 v89, s[6:7], 1.0, v81, 1.0
	v_fma_f32 v149, -v90, v95, 1.0
	v_fmac_f32_e32 v94, v148, v94
	v_fma_f32 v151, -v86, v147, v87
	v_fmac_f32_e32 v146, v150, v92
	v_div_scale_f32 v91, s[8:9], 1.0, v85, 1.0
	v_fmac_f32_e32 v95, v149, v95
	v_mul_f32_e32 v148, v89, v94
	v_fmac_f32_e32 v147, v151, v93
	v_fma_f32 v80, -v80, v146, v83
	v_mul_f32_e32 v149, v91, v95
	v_fma_f32 v152, -v88, v148, v89
	v_fma_f32 v83, -v86, v147, v87
	v_div_fmas_f32 v80, v80, v92, v146
	s_mov_b64 vcc, s[4:5]
	v_fma_f32 v153, -v90, v149, v91
	v_fmac_f32_e32 v148, v152, v94
	v_div_fixup_f32 v80, v80, v82, 1.0
	v_div_fmas_f32 v82, v83, v93, v147
	v_fmac_f32_e32 v149, v153, v95
	v_fma_f32 v86, -v88, v148, v89
	v_div_fixup_f32 v82, v82, v84, 1.0
	s_mov_b64 vcc, s[6:7]
	v_fma_f32 v87, -v90, v149, v91
	v_pk_mul_f32 v[68:69], v[68:69], v[80:81] op_sel_hi:[1,0]
	v_pk_mul_f32 v[70:71], v[70:71], v[80:81] op_sel_hi:[1,0]
	v_pk_mul_f32 v[72:73], v[72:73], v[80:81] op_sel_hi:[1,0]
	v_pk_mul_f32 v[74:75], v[74:75], v[80:81] op_sel_hi:[1,0]
	v_pk_mul_f32 v[76:77], v[76:77], v[80:81] op_sel_hi:[1,0]
	v_pk_mul_f32 v[78:79], v[78:79], v[80:81] op_sel_hi:[1,0]
	v_pk_mul_f32 v[64:65], v[64:65], v[80:81] op_sel_hi:[1,0]
	v_pk_mul_f32 v[66:67], v[66:67], v[80:81] op_sel_hi:[1,0]
	v_div_fmas_f32 v80, v86, v94, v148
	v_pk_mul_f32 v[62:63], v[62:63], v[82:83] op_sel_hi:[1,0]
; __device__ __forceinline__ unsigned cvt_pk_bf16(float lo, float hi) { unsigned r; asm volatile("v_cvt_pk_bf16_f32 %0, %1, %2" : "=v"(r) : "v"(lo), "v"(hi)); return r; }
; __device__ __forceinline__ void pass_h_fold(const float* src, const float* g, const float* mod, bf16_t* H, bf16_t* HE, bf16_t* HO) {
;     ...
;                 for (int j = 0; j < 4; ++j) { const f32x4 h0 = (v[q][0][j] * r0) * mul[j] + sh[j], h1 = (v[q][1][j] * r1) * mul[j] + sh[j];
;                     u32x2 w; w.x = cvt_pk_bf16(h0[0], h0[1]); w.y = cvt_pk_bf16(h0[2], h0[3]); o0[64 * j] = w;
;                     w.x = cvt_pk_bf16(h1[0], h1[1]); w.y = cvt_pk_bf16(h1[2], h1[3]); o1[64 * j] = w;
;                     const f32x4 e = (s == 0) ? h0 : h0 + h1, o = (s == 0) ? (f32x4){0.f, 0.f, 0.f, 0.f} : h0 - h1;
;                     w.x = cvt_pk_bf16(e[0], e[1]); w.y = cvt_pk_bf16(e[2], e[3]); oe[64 * j] = w;
;                     w.x = cvt_pk_bf16(o[0], o[1]); w.y = cvt_pk_bf16(o[2], o[3]); oo[64 * j] = w; } }
	s_mov_b64 vcc, s[8:9]
	v_pk_fma_f32 v[70:71], v[130:131], v[70:71], v[30:31]
	v_div_fixup_f32 v80, v80, v81, 1.0
	v_div_fmas_f32 v81, v87, v95, v149
	v_pk_fma_f32 v[62:63], v[130:131], v[62:63], v[30:31]
	v_pk_mul_f32 v[60:61], v[60:61], v[82:83] op_sel_hi:[1,0]
	v_div_fixup_f32 v84, v81, v85, 1.0
	v_sub_f32_e32 v85, v70, v62
	v_pk_fma_f32 v[68:69], v[132:133], v[68:69], v[28:29]
	v_pk_mul_f32 v[52:53], v[52:53], v[82:83] op_sel_hi:[1,0]
	v_pk_mul_f32 v[54:55], v[54:55], v[82:83] op_sel_hi:[1,0]
	v_pk_mul_f32 v[56:57], v[56:57], v[82:83] op_sel_hi:[1,0]
	v_pk_mul_f32 v[58:59], v[58:59], v[82:83] op_sel_hi:[1,0]
	v_pk_mul_f32 v[48:49], v[48:49], v[82:83] op_sel_hi:[1,0]
	v_pk_mul_f32 v[50:51], v[50:51], v[82:83] op_sel_hi:[1,0]
	v_pk_fma_f32 v[60:61], v[132:133], v[60:61], v[28:29]
	v_cvt_pk_bf16_f32 v82, v68, v69
	v_cvt_pk_bf16_f32 v83, v70, v71
	v_pk_mul_f32 v[32:33], v[32:33], v[80:81] op_sel_hi:[1,0]
	v_pk_mul_f32 v[34:35], v[34:35], v[80:81] op_sel_hi:[1,0]
	v_pk_mul_f32 v[40:41], v[40:41], v[80:81] op_sel_hi:[1,0]
	v_pk_mul_f32 v[42:43], v[42:43], v[80:81] op_sel_hi:[1,0]
	v_pk_mul_f32 v[44:45], v[44:45], v[80:81] op_sel_hi:[1,0]
	v_pk_mul_f32 v[46:47], v[46:47], v[80:81] op_sel_hi:[1,0]
	v_pk_mul_f32 v[36:37], v[36:37], v[80:81] op_sel_hi:[1,0]
	v_pk_mul_f32 v[38:39], v[38:39], v[80:81] op_sel_hi:[1,0]
	global_store_dwordx2 v[126:127], v[82:83], off sc1
	v_cvt_pk_bf16_f32 v80, v60, v61
	v_cvt_pk_bf16_f32 v81, v62, v63
	v_pk_mul_f32 v[12:13], v[12:13], v[84:85] op_sel_hi:[1,0]
	v_pk_fma_f32 v[76:77], v[140:141], v[76:77], v[16:17]
	v_pk_fma_f32 v[56:57], v[140:141], v[56:57], v[16:17]
	v_pk_add_f32 v[82:83], v[70:71], v[62:63]
	v_pk_add_f32 v[86:87], v[68:69], v[60:61]
	v_sub_f32_e32 v92, v71, v63
	v_sub_f32_e32 v93, v68, v60
	v_sub_f32_e32 v94, v69, v61
	v_pk_fma_f32 v[44:45], v[140:141], v[44:45], v[16:17]
	global_store_dwordx2 v[128:129], v[80:81], off sc1
	v_cvt_pk_bf16_f32 v80, v86, v87
	v_cvt_pk_bf16_f32 v81, v82, v83
	v_pk_fma_f32 v[12:13], v[140:141], v[12:13], v[16:17]
	global_store_dwordx2 v[124:125], v[80:81], off sc1
	v_cvt_pk_bf16_f32 v16, v93, v94
	v_cvt_pk_bf16_f32 v17, v85, v92
	v_pk_fma_f32 v[74:75], v[134:135], v[74:75], v[22:23]
	v_pk_fma_f32 v[72:73], v[136:137], v[72:73], v[20:21]
	global_store_dwordx2 v[122:123], v[16:17], off sc1
	v_cvt_pk_bf16_f32 v16, v72, v73
	v_cvt_pk_bf16_f32 v17, v74, v75
	v_pk_fma_f32 v[54:55], v[134:135], v[54:55], v[22:23]
	v_pk_fma_f32 v[52:53], v[136:137], v[52:53], v[20:21]
	global_store_dwordx2 v[126:127], v[16:17], off offset:512 sc1
	v_cvt_pk_bf16_f32 v16, v52, v53
	v_cvt_pk_bf16_f32 v17, v54, v55
	v_pk_add_f32 v[60:61], v[74:75], v[54:55]
	v_pk_add_f32 v[62:63], v[72:73], v[52:53]
	global_store_dwordx2 v[128:129], v[16:17], off offset:512 sc1
	v_cvt_pk_bf16_f32 v16, v62, v63
	v_cvt_pk_bf16_f32 v17, v60, v61
	v_sub_f32_e32 v95, v74, v54
	v_sub_f32_e32 v146, v75, v55
	v_sub_f32_e32 v147, v72, v52
	v_sub_f32_e32 v148, v73, v53
	global_store_dwordx2 v[124:125], v[16:17], off offset:512 sc1
	v_cvt_pk_bf16_f32 v16, v147, v148
	v_cvt_pk_bf16_f32 v17, v95, v146
	v_pk_fma_f32 v[78:79], v[138:139], v[78:79], v[18:19]
	global_store_dwordx2 v[122:123], v[16:17], off offset:512 sc1
	v_cvt_pk_bf16_f32 v16, v76, v77
	v_cvt_pk_bf16_f32 v17, v78, v79
	v_pk_fma_f32 v[58:59], v[138:139], v[58:59], v[18:19]
	global_store_dwordx2 v[126:127], v[16:17], off offset:1024 sc1
	v_cvt_pk_bf16_f32 v16, v56, v57
	v_cvt_pk_bf16_f32 v17, v58, v59
	v_pk_add_f32 v[68:69], v[78:79], v[58:59]
	v_pk_add_f32 v[70:71], v[76:77], v[56:57]
	global_store_dwordx2 v[128:129], v[16:17], off offset:1024 sc1
	v_cvt_pk_bf16_f32 v16, v70, v71
	v_cvt_pk_bf16_f32 v17, v68, v69
	v_sub_f32_e32 v149, v78, v58
	v_sub_f32_e32 v150, v79, v59
	v_sub_f32_e32 v151, v76, v56
	v_sub_f32_e32 v152, v77, v57
	global_store_dwordx2 v[124:125], v[16:17], off offset:1024 sc1
	v_cvt_pk_bf16_f32 v16, v151, v152
	v_cvt_pk_bf16_f32 v17, v149, v150
	v_pk_fma_f32 v[66:67], v[142:143], v[66:67], v[26:27]
	v_pk_fma_f32 v[64:65], v[144:145], v[64:65], v[24:25]
	global_store_dwordx2 v[122:123], v[16:17], off offset:1024 sc1
	v_cvt_pk_bf16_f32 v16, v64, v65
	v_cvt_pk_bf16_f32 v17, v66, v67
	v_pk_fma_f32 v[50:51], v[142:143], v[50:51], v[26:27]
	v_pk_fma_f32 v[48:49], v[144:145], v[48:49], v[24:25]
	global_store_dwordx2 v[126:127], v[16:17], off offset:1536 sc1
	v_cvt_pk_bf16_f32 v16, v48, v49
	v_cvt_pk_bf16_f32 v17, v50, v51
	v_pk_add_f32 v[88:89], v[66:67], v[50:51]
; __device__ __forceinline__ unsigned cvt_pk_bf16(float lo, float hi) { unsigned r; asm volatile("v_cvt_pk_bf16_f32 %0, %1, %2" : "=v"(r) : "v"(lo), "v"(hi)); return r; }
; __device__ __forceinline__ void pass_h_fold(const float* src, const float* g, const float* mod, bf16_t* H, bf16_t* HE, bf16_t* HO) {
;     ...
;                 for (int j = 0; j < 4; ++j) { const f32x4 h0 = (v[q][0][j] * r0) * mul[j] + sh[j], h1 = (v[q][1][j] * r1) * mul[j] + sh[j];
;                     u32x2 w; w.x = cvt_pk_bf16(h0[0], h0[1]); w.y = cvt_pk_bf16(h0[2], h0[3]); o0[64 * j] = w;
;                     w.x = cvt_pk_bf16(h1[0], h1[1]); w.y = cvt_pk_bf16(h1[2], h1[3]); o1[64 * j] = w;
;                     const f32x4 e = (s == 0) ? h0 : h0 + h1, o = (s == 0) ? (f32x4){0.f, 0.f, 0.f, 0.f} : h0 - h1;
;                     w.x = cvt_pk_bf16(e[0], e[1]); w.y = cvt_pk_bf16(e[2], e[3]); oe[64 * j] = w;
;                     w.x = cvt_pk_bf16(o[0], o[1]); w.y = cvt_pk_bf16(o[2], o[3]); oo[64 * j] = w; } }
	v_pk_add_f32 v[90:91], v[64:65], v[48:49]
	v_pk_mul_f32 v[4:5], v[4:5], v[84:85] op_sel_hi:[1,0]
	global_store_dwordx2 v[128:129], v[16:17], off offset:1536 sc1
	v_cvt_pk_bf16_f32 v16, v90, v91
	v_cvt_pk_bf16_f32 v17, v88, v89
	v_sub_f32_e32 v153, v66, v50
	v_sub_f32_e32 v154, v67, v51
	v_sub_f32_e32 v155, v64, v48
	v_sub_f32_e32 v156, v65, v49
	v_pk_fma_f32 v[32:33], v[132:133], v[32:33], v[28:29]
	v_pk_mul_f32 v[6:7], v[6:7], v[84:85] op_sel_hi:[1,0]
	v_pk_mul_f32 v[8:9], v[8:9], v[84:85] op_sel_hi:[1,0]
	v_pk_fma_f32 v[4:5], v[132:133], v[4:5], v[28:29]
	global_store_dwordx2 v[124:125], v[16:17], off offset:1536 sc1
	v_cvt_pk_bf16_f32 v16, v155, v156
	v_cvt_pk_bf16_f32 v17, v153, v154
	v_pk_fma_f32 v[34:35], v[130:131], v[34:35], v[30:31]
	v_pk_fma_f32 v[40:41], v[136:137], v[40:41], v[20:21]
	v_pk_mul_f32 v[10:11], v[10:11], v[84:85] op_sel_hi:[1,0]
	v_pk_mul_f32 v[14:15], v[14:15], v[84:85] op_sel_hi:[1,0]
	v_pk_mul_f32 v[0:1], v[0:1], v[84:85] op_sel_hi:[1,0]
	v_pk_mul_f32 v[2:3], v[2:3], v[84:85] op_sel_hi:[1,0]
	v_pk_fma_f32 v[6:7], v[130:131], v[6:7], v[30:31]
	v_pk_fma_f32 v[8:9], v[136:137], v[8:9], v[20:21]
	v_pk_add_f32 v[20:21], v[32:33], v[4:5]
	v_sub_f32_e32 v84, v32, v4
	v_sub_f32_e32 v85, v33, v5
	global_store_dwordx2 v[122:123], v[16:17], off offset:1536 sc1
	v_cvt_pk_bf16_f32 v16, v32, v33
	v_cvt_pk_bf16_f32 v17, v34, v35
	global_store_dwordx2 v[118:119], v[16:17], off sc1
	v_cvt_pk_bf16_f32 v4, v4, v5
	v_cvt_pk_bf16_f32 v5, v6, v7
	v_pk_fma_f32 v[46:47], v[138:139], v[46:47], v[18:19]
	v_pk_fma_f32 v[14:15], v[138:139], v[14:15], v[18:19]
	v_pk_add_f32 v[18:19], v[34:35], v[6:7]
	global_store_dwordx2 v[120:121], v[4:5], off sc1
	v_cvt_pk_bf16_f32 v4, v20, v21
	v_cvt_pk_bf16_f32 v5, v18, v19
	v_sub_f32_e32 v82, v34, v6
	v_sub_f32_e32 v83, v35, v7
	global_store_dwordx2 v[116:117], v[4:5], off sc1
	v_cvt_pk_bf16_f32 v4, v84, v85
	v_cvt_pk_bf16_f32 v5, v82, v83
	v_pk_fma_f32 v[42:43], v[134:135], v[42:43], v[22:23]
	global_store_dwordx2 v[114:115], v[4:5], off sc1
	v_cvt_pk_bf16_f32 v4, v40, v41
	v_cvt_pk_bf16_f32 v5, v42, v43
	v_pk_fma_f32 v[10:11], v[134:135], v[10:11], v[22:23]
	global_store_dwordx2 v[118:119], v[4:5], off offset:512 sc1
	v_cvt_pk_bf16_f32 v4, v8, v9
	v_cvt_pk_bf16_f32 v5, v10, v11
	v_pk_fma_f32 v[36:37], v[144:145], v[36:37], v[24:25]
	v_pk_fma_f32 v[0:1], v[144:145], v[0:1], v[24:25]
	v_pk_add_f32 v[22:23], v[42:43], v[10:11]
	v_pk_add_f32 v[24:25], v[40:41], v[8:9]
	global_store_dwordx2 v[120:121], v[4:5], off offset:512 sc1
	v_cvt_pk_bf16_f32 v4, v24, v25
	v_cvt_pk_bf16_f32 v5, v22, v23
	v_sub_f32_e32 v86, v42, v10
	v_sub_f32_e32 v87, v43, v11
	v_sub_f32_e32 v92, v40, v8
	v_sub_f32_e32 v93, v41, v9
	global_store_dwordx2 v[116:117], v[4:5], off offset:512 sc1
	v_cvt_pk_bf16_f32 v4, v92, v93
	v_cvt_pk_bf16_f32 v5, v86, v87
	global_store_dwordx2 v[114:115], v[4:5], off offset:512 sc1
	v_cvt_pk_bf16_f32 v4, v44, v45
	v_cvt_pk_bf16_f32 v5, v46, v47
	global_store_dwordx2 v[118:119], v[4:5], off offset:1024 sc1
	v_cvt_pk_bf16_f32 v4, v12, v13
	v_cvt_pk_bf16_f32 v5, v14, v15
	v_pk_fma_f32 v[38:39], v[142:143], v[38:39], v[26:27]
	v_pk_fma_f32 v[2:3], v[142:143], v[2:3], v[26:27]
	v_pk_add_f32 v[26:27], v[46:47], v[14:15]
	v_pk_add_f32 v[28:29], v[44:45], v[12:13]
	global_store_dwordx2 v[120:121], v[4:5], off offset:1024 sc1
	v_cvt_pk_bf16_f32 v4, v28, v29
	v_cvt_pk_bf16_f32 v5, v26, v27
	v_sub_f32_e32 v94, v46, v14
	v_sub_f32_e32 v130, v47, v15
	v_sub_f32_e32 v131, v44, v12
	v_sub_f32_e32 v132, v45, v13
	global_store_dwordx2 v[116:117], v[4:5], off offset:1024 sc1
	v_cvt_pk_bf16_f32 v4, v131, v132
	v_cvt_pk_bf16_f32 v5, v94, v130
	v_pk_add_f32 v[80:81], v[36:37], v[0:1]
	v_sub_f32_e32 v135, v36, v0
	v_sub_f32_e32 v136, v37, v1
	global_store_dwordx2 v[114:115], v[4:5], off offset:1024 sc1
	v_cvt_pk_bf16_f32 v4, v36, v37
	v_cvt_pk_bf16_f32 v5, v38, v39
	global_store_dwordx2 v[118:119], v[4:5], off offset:1536 sc1
	v_cvt_pk_bf16_f32 v0, v0, v1
	v_cvt_pk_bf16_f32 v1, v2, v3
	v_pk_add_f32 v[30:31], v[38:39], v[2:3]
	global_store_dwordx2 v[120:121], v[0:1], off offset:1536 sc1
	v_cvt_pk_bf16_f32 v0, v80, v81
	v_cvt_pk_bf16_f32 v1, v30, v31
	v_sub_f32_e32 v133, v38, v2
	v_sub_f32_e32 v134, v39, v3
	global_store_dwordx2 v[116:117], v[0:1], off offset:1536 sc1
	v_cvt_pk_bf16_f32 v0, v135, v136
	v_cvt_pk_bf16_f32 v1, v133, v134
	global_store_dwordx2 v[114:115], v[0:1], off offset:1536 sc1
	s_andn2_b64 exec, exec, s[22:23]
	s_cbranch_execnz .LBB0_99
